# attention: unmasked key blocks (ctx, current) run an inner-loop copy without window-mask arithmetic
# speedup vs baseline: 1.0192x; 1.0192x over previous
.LBB0_493:
	s_add_i32 s11, s10, s20
	s_cmp_lt_u32 s11, 2
	s_cselect_b64 s[12:13], -1, 0
	s_add_i32 s21, s19, s11
	s_cmpk_lt_u32 s21, 0x80
	s_cselect_b64 s[22:23], -1, 0
	s_or_b64 s[12:13], s[12:13], s[22:23]
	s_andn2_b64 vcc, exec, s[12:13]
	s_cbranch_vccnz .LBB0_492
	s_cmp_eq_u32 s11, 4
	v_mov_b32_e32 v66, v166
	v_mov_b32_e32 v67, v165
	s_cselect_b64 s[12:13], -1, 0
	s_cmp_lg_u32 s11, 2
	v_cndmask_b32_e64 v68, 0, -1, s[12:13]
	s_cselect_b64 vcc, -1, 0
	v_lshlrev_b32_e32 v66, 2, v66
	v_cndmask_b32_e32 v202, 1, v68, vcc
	v_add_u32_e32 v68, v170, v66
	v_sub_u32_e32 v203, v68, v67
	v_add_u32_e32 v68, v171, v66
	v_sub_u32_e32 v68, v68, v67
	v_mul_lo_u32 v204, v202, v68
	v_add_u32_e32 v68, v172, v66
	v_sub_u32_e32 v68, v68, v67
	v_mul_lo_u32 v206, v202, v68
	v_add_u32_e32 v68, v173, v66
	v_sub_u32_e32 v68, v68, v67
	v_mul_lo_u32 v207, v202, v68
	v_add_u32_e32 v68, v174, v66
	v_sub_u32_e32 v68, v68, v67
	v_mul_lo_u32 v208, v202, v68
	v_add_u32_e32 v68, v175, v66
	v_add_u32_e32 v66, v176, v66
	v_sub_u32_e32 v68, v68, v67
	v_sub_u32_e32 v66, v66, v67
	v_lshlrev_b32_e32 v205, 5, v202
	v_mul_lo_u32 v209, v202, v68
	v_mul_lo_u32 v210, v202, v66
	s_cmp_eq_u32 s11, 2
	s_cbranch_scc1 .Lattn_masked
	s_cmp_eq_u32 s11, 4
	s_cbranch_scc1 .Lattn_masked
	s_mov_b32 s11, 0
	v_mov_b32_e32 v211, 0
	v_mov_b32_e32 v212, v0
	v_mov_b32_e32 v213, v177
	s_branch .Lattn_nm
.Lattn_masked:
	s_mov_b32 s11, 0
	v_mov_b32_e32 v211, 0
	v_mov_b32_e32 v212, v0
	v_mov_b32_e32 v213, v177

.Lattn_nm:
	v_add_u32_e32 v66, 0x2000, v213
	ds_read_b128 v[152:155], v212
	ds_read_b128 v[156:159], v212 offset:32
	ds_read_b128 v[160:163], v212 offset:64
	ds_read_b128 v[224:227], v212 offset:96
	ds_read2_b64 v[114:117], v213 offset1:2
	ds_read2_b64 v[118:121], v213 offset0:4 offset1:6
	ds_read2_b64 v[126:129], v66 offset0:64 offset1:66
	ds_read2_b64 v[122:125], v66 offset0:68 offset1:70
	s_waitcnt vmcnt(7) lgkmcnt(7)
	v_mfma_f32_32x32x16_bf16 v[66:81], v[152:155], v[82:85], 0
	v_add_u32_e32 v223, s11, v203
	s_add_i32 s11, s11, 32
	v_add_u32_e32 v213, 64, v213
	v_add_u32_e32 v212, 0x1200, v212
	s_cmpk_lg_i32 s11, 0x80
	s_waitcnt vmcnt(6) lgkmcnt(6)
	v_mfma_f32_32x32x16_bf16 v[66:81], v[156:159], v[86:89], v[66:81]
	s_waitcnt vmcnt(5) lgkmcnt(5)
	v_mfma_f32_32x32x16_bf16 v[66:81], v[160:163], v[90:93], v[66:81]
	s_waitcnt vmcnt(4) lgkmcnt(4)
	v_mfma_f32_32x32x16_bf16 v[66:81], v[224:227], v[94:97], v[66:81]
	s_nop 11
	v_mul_f32_e32 v66, 0x3fb8aa3b, v66
	v_exp_f32_e32 v148, v66
	v_mul_f32_e32 v66, 0x3fb8aa3b, v67
	v_exp_f32_e32 v180, v66
	v_mul_f32_e32 v66, 0x3fb8aa3b, v68
	v_exp_f32_e32 v181, v66
	v_mul_f32_e32 v66, 0x3fb8aa3b, v69
	v_exp_f32_e32 v182, v66
	v_mul_f32_e32 v66, 0x3fb8aa3b, v70
	v_exp_f32_e32 v183, v66
	v_mul_f32_e32 v66, 0x3fb8aa3b, v71
	v_exp_f32_e32 v184, v66
	v_mul_f32_e32 v66, 0x3fb8aa3b, v72
	v_exp_f32_e32 v149, v66
	v_mul_f32_e32 v66, 0x3fb8aa3b, v73
	v_exp_f32_e32 v222, v66
	v_mul_f32_e32 v66, 0x3fb8aa3b, v74
	v_exp_f32_e32 v221, v66
	v_mul_f32_e32 v66, 0x3fb8aa3b, v75
	v_exp_f32_e32 v220, v66
	v_mul_f32_e32 v66, 0x3fb8aa3b, v76
	v_exp_f32_e32 v219, v66
	v_mul_f32_e32 v66, 0x3fb8aa3b, v77
	v_exp_f32_e32 v218, v66
	v_mul_f32_e32 v66, 0x3fb8aa3b, v78
	v_exp_f32_e32 v217, v66
	v_mul_f32_e32 v66, 0x3fb8aa3b, v79
	v_exp_f32_e32 v216, v66
	v_mul_f32_e32 v66, 0x3fb8aa3b, v80
	v_exp_f32_e32 v215, v66
	v_mul_f32_e32 v66, 0x3fb8aa3b, v81
	v_exp_f32_e32 v214, v66
	s_waitcnt vmcnt(3)
	v_mfma_f32_32x32x16_bf16 v[66:81], v[152:155], v[98:101], 0
	s_waitcnt vmcnt(2)
	v_mfma_f32_32x32x16_bf16 v[66:81], v[156:159], v[102:105], v[66:81]
	s_waitcnt vmcnt(1)
	v_mfma_f32_32x32x16_bf16 v[66:81], v[160:163], v[106:109], v[66:81]
	s_waitcnt vmcnt(0)
	v_mfma_f32_32x32x16_bf16 v[66:81], v[224:227], v[110:113], v[66:81]
	s_nop 9
	s_nop 1
	v_mul_f32_e32 v70, 0x3fb8aa3b, v70
	v_exp_f32_e32 v158, v70
	v_mul_f32_e32 v70, 0x3fb8aa3b, v71
	v_mul_f32_e32 v66, 0x3fb8aa3b, v66
	v_exp_f32_e32 v71, v70
	v_exp_f32_e32 v66, v66
	v_mul_f32_e32 v67, 0x3fb8aa3b, v67
	v_exp_f32_e32 v67, v67
	v_mov_b32_e32 v70, v149
	v_mul_f32_e32 v68, 0x3fb8aa3b, v68
	v_exp_f32_e32 v68, v68
	v_mov_b32_e32 v149, v66
	v_mul_f32_e32 v69, 0x3fb8aa3b, v69
	v_mov_b32_e32 v148, v148
	v_exp_f32_e32 v69, v69
	v_mov_b32_e32 v153, v67
	v_pk_add_f32 v[162:163], v[148:149], 0 op_sel_hi:[1,0]
	v_mov_b32_e32 v152, v180
	v_mov_b32_e32 v155, v68
	v_mov_b32_e32 v154, v181
	v_cvt_pk_bf16_f32 v66, v148, v152
	v_pk_add_f32 v[162:163], v[152:153], v[162:163]
	v_mov_b32_e32 v157, v69
	v_mov_b32_e32 v156, v182
	v_mov_b32_e32 v159, v158
	v_mov_b32_e32 v158, v183
	v_pk_add_f32 v[162:163], v[154:155], v[162:163]
	v_cvt_pk_bf16_f32 v67, v154, v156
	v_mov_b32_e32 v161, v71
	v_mul_f32_e32 v71, 0x3fb8aa3b, v72
	v_exp_f32_e32 v71, v71
	v_mul_f32_e32 v72, 0x3fb8aa3b, v73
	v_exp_f32_e32 v148, v72
	v_mul_f32_e32 v72, 0x3fb8aa3b, v74
	v_mov_b32_e32 v160, v184
	v_exp_f32_e32 v74, v72
	v_mul_f32_e32 v72, 0x3fb8aa3b, v75
	v_mov_b32_e32 v71, v71
	v_exp_f32_e32 v75, v72
	v_mul_f32_e32 v72, 0x3fb8aa3b, v76
	v_pk_add_f32 v[162:163], v[156:157], v[162:163]
	v_exp_f32_e32 v156, v72
	v_mul_f32_e32 v72, 0x3fb8aa3b, v77
	v_mov_b32_e32 v77, v148
	v_cvt_pk_bf16_f32 v68, v158, v160
	v_pk_add_f32 v[162:163], v[158:159], v[162:163]
	v_exp_f32_e32 v158, v72
	v_mul_f32_e32 v72, 0x3fb8aa3b, v78
	v_mov_b32_e32 v76, v222
	v_pk_add_f32 v[162:163], v[160:161], v[162:163]
	v_exp_f32_e32 v160, v72
	v_mul_f32_e32 v72, 0x3fb8aa3b, v79
	v_mov_b32_e32 v79, v74
	v_exp_f32_e32 v184, v72
	v_mul_f32_e32 v72, 0x3fb8aa3b, v80
	v_mov_b32_e32 v78, v221
	v_exp_f32_e32 v226, v72
	v_mul_f32_e32 v72, 0x3fb8aa3b, v81
	v_mov_b32_e32 v81, v75
	v_mov_b32_e32 v80, v220
	v_exp_f32_e32 v227, v72
	v_pk_add_f32 v[72:73], v[70:71], v[162:163]
	v_mov_b32_e32 v163, v156
	v_mov_b32_e32 v162, v219
	v_mov_b32_e32 v181, v158
	v_mov_b32_e32 v180, v218
	v_mov_b32_e32 v183, v160
	v_mov_b32_e32 v182, v217
	v_mov_b32_e32 v185, v184
	v_mov_b32_e32 v184, v216
	v_mov_b32_e32 v217, v226
	v_pk_add_f32 v[72:73], v[76:77], v[72:73]
	v_mov_b32_e32 v216, v215
	v_cvt_pk_bf16_f32 v69, v70, v76
	v_pk_add_f32 v[72:73], v[78:79], v[72:73]
	v_pk_add_f32 v[72:73], v[80:81], v[72:73]
	s_waitcnt lgkmcnt(3)
	v_mfma_f32_32x32x16_bf16 v[34:49], v[66:69], v[114:117], v[34:49]
	v_add_f32_e64 v72, v162, v72
	v_add_f32_e64 v73, v163, v73
	v_mov_b32_e32 v215, v227
	v_add_f32_e64 v72, v180, v72
	v_add_f32_e64 v73, v181, v73
	v_pk_add_f32 v[72:73], v[182:183], v[72:73]
	v_cvt_pk_bf16_f32 v74, v182, v184
	v_pk_add_f32 v[72:73], v[184:185], v[72:73]
	s_waitcnt lgkmcnt(1)
	v_mfma_f32_32x32x16_bf16 v[50:65], v[66:69], v[126:129], v[50:65]
	v_cvt_pk_bf16_f32 v66, v149, v153
	v_cvt_pk_bf16_f32 v67, v155, v157
	v_cvt_pk_bf16_f32 v68, v159, v161
	v_cvt_pk_bf16_f32 v69, v71, v77
	v_add_f32_e64 v72, v216, v72
	v_add_f32_e64 v73, v217, v73
	v_mov_b32_e32 v214, v214
	v_pk_add_f32 v[218:219], v[214:215], v[72:73]
	v_cvt_pk_bf16_f32 v72, v78, v80
	v_cvt_pk_bf16_f32 v73, v162, v180
	v_cvt_pk_bf16_f32 v75, v216, v214
	v_mfma_f32_32x32x16_bf16 v[18:33], v[66:69], v[114:117], v[18:33]
	v_cvt_pk_bf16_f32 v70, v79, v81
	v_cvt_pk_bf16_f32 v71, v163, v181
	v_add_f32_e64 v130, v130, v218
	v_add_f32_e64 v131, v131, v219
	v_mfma_f32_32x32x16_bf16 v[2:17], v[66:69], v[126:129], v[2:17]
	v_mfma_f32_32x32x16_bf16 v[34:49], v[72:75], v[118:121], v[34:49]
	s_waitcnt lgkmcnt(0)
	v_mfma_f32_32x32x16_bf16 v[50:65], v[72:75], v[122:125], v[50:65]
	v_cvt_pk_bf16_f32 v72, v183, v185
	v_cvt_pk_bf16_f32 v73, v217, v215
	s_nop 1
	v_mfma_f32_32x32x16_bf16 v[18:33], v[70:73], v[118:121], v[18:33]
	v_mfma_f32_32x32x16_bf16 v[2:17], v[70:73], v[122:125], v[2:17]
	s_cbranch_scc1 .Lattn_nm
	s_branch .LBB0_492
